# P8 transposed-V LDS tile: 16-byte chunk index XORed with (row>>4)&7 on writer and reader, so the 2-byte transposing writes spread over 32 banks instead of 4
# speedup vs baseline: 1.0483x; 1.0040x over previous
.LBB0_862:
	s_or_b64 exec, exec, s[0:1]
	s_cmpk_lt_i32 s2, 0x1000
	s_cselect_b64 s[0:1], -1, 0
	v_mov_b32_e32 v0, v191
	s_and_b64 vcc, exec, s[0:1]
	s_waitcnt lgkmcnt(0)
	s_barrier
	s_cbranch_vccz .LBB0_867
	v_lshlrev_b32_e32 v1, 3, v0
	v_and_b32_e32 v1, 0x78, v1
	v_lshlrev_b32_e32 v2, 1, v1
	v_mov_b32_e32 v3, 0
	v_and_b32_e32 v4, 0x7f, v0
	v_lshl_add_u64 v[8:9], s[14:15], 0, v[2:3]
	v_lshlrev_b32_e32 v2, 2, v4
	v_lshl_add_u64 v[10:11], s[30:31], 0, v[2:3]
	v_add_u32_e32 v22, 16, v2
	v_mul_u32_u24_e32 v2, 0x8c, v4
	v_ashrrev_i32_e32 v4, 3, v0
	v_ashrrev_i32_e32 v5, 7, v0
	v_lshlrev_b32_e32 v4, 1, v4
	v_lshlrev_b32_e32 v20, 4, v5
	v_cmp_lt_i32_e64 s[4:5], 0, v5
	v_cmp_lt_i32_e64 s[6:7], 1, v5
	v_cmp_lt_i32_e64 s[8:9], 2, v5
	v_cmp_lt_i32_e64 s[10:11], 3, v5
	v_and_b32_e32 v4, 0xffffffe0, v4
	v_ashrrev_i32_e32 v5, 2, v0
	v_add3_u32 v23, v22, v2, v4
	v_and_b32_e32 v4, -16, v5
	v_bfi_b32 v5, -16, v5, v0
	s_movk_i32 s18, 0x90
	v_mul_lo_u32 v5, v5, s18
	v_bfe_u32 v2, v0, 4, 2
	v_add_u32_e32 v7, 16, v5
	v_ashrrev_i32_e32 v5, 31, v4
	v_ashrrev_i32_e32 v13, 4, v0
	v_and_b32_e32 v12, 15, v0
	v_lshlrev_b32_e32 v17, 4, v2
	v_lshl_add_u64 v[4:5], v[4:5], 1, s[28:29]
	v_lshlrev_b32_e32 v2, 3, v2
	s_add_u32 s16, s84, 0x1db00000
	s_movk_i32 s12, 0x80
	v_lshl_add_u32 v6, v13, 1, 16
	v_add_u32_e32 v18, 16, v17
	v_lshl_add_u64 v[14:15], v[4:5], 0, v[2:3]
	v_mul_u32_u24_e32 v1, 0x90, v1
	v_mul_u32_u24_e32 v2, 0x90, v12
	s_addc_u32 s17, s85, 0
	v_lshl_add_u32 v21, v0, 2, 16
	s_mov_b32 s19, 0
	v_cmp_gt_u32_e64 s[12:13], s12, v0
	s_lshl_b32 s24, s2, 6
	s_lshl_b32 s25, s86, 6
	v_lshl_add_u32 v16, s2, 7, v0
	s_lshl_b32 s27, s86, 7
	s_mov_b32 s34, 0x10000
	v_add_u32_e32 v24, v6, v1
	v_add_u32_e32 v25, v7, v17
	v_add_u32_e32 v26, v18, v2
	v_bfe_u32 v99, v191, 1, 3
	v_bfe_u32 v100, v191, 7, 2
	v_xor_b32_e32 v101, v100, v99
	v_sub_u32_e32 v101, v101, v100
	v_lshl_add_u32 v98, v101, 4, v24
	v_xor_b32_e32 v101, 4, v100
	v_xor_b32_e32 v101, v101, v99
	v_sub_u32_e32 v101, v101, v100
	v_add_u32_e32 v101, -4, v101
	v_lshl_add_u32 v97, v101, 4, v24
	v_bfe_u32 v99, v191, 4, 2
	v_lshlrev_b32_e32 v100, 4, v99
	v_sub_u32_e32 v102, v26, v100
	v_xor_b32_e32 v100, 1, v99
	v_lshl_add_u32 v103, v100, 4, v102
	v_xor_b32_e32 v100, 2, v99
	v_lshl_add_u32 v104, v100, 4, v102
	v_xor_b32_e32 v100, 3, v99
	v_lshl_add_u32 v105, v100, 4, v102
	s_movk_i32 s35, 0x2000
	s_movk_i32 s36, 0x4000
	s_movk_i32 s37, 0x6000
	s_mov_b32 s38, s97
	s_mov_b32 s20, s2
	s_and_b32 s18, s38, 0xffffc000
	s_and_b32 s21, s24, 0x3fc0
	s_or_b32 s21, s18, s21
	s_lshr_b32 s18, s20, 1
	s_and_b32 s22, s18, 0x380
	v_add_u32_e32 v2, s21, v20
	s_lshl_b32 s18, s22, 1
	v_or_b32_e32 v38, 7, v2
	v_lshl_add_u64 v[0:1], v[8:9], 0, s[18:19]
	s_lshl_b32 s18, s22, 2
	v_ashrrev_i32_e32 v3, 31, v2
	v_or_b32_e32 v18, 1, v2
	v_or_b32_e32 v28, 2, v2
	v_or_b32_e32 v30, 3, v2
	v_or_b32_e32 v32, 4, v2
	v_or_b32_e32 v34, 5, v2
	v_or_b32_e32 v36, 6, v2
	v_ashrrev_i32_e32 v39, 31, v38
	v_lshl_add_u64 v[4:5], v[10:11], 0, s[18:19]
	v_lshlrev_b64 v[6:7], 12, v[2:3]
	v_ashrrev_i32_e32 v19, 31, v18
	v_ashrrev_i32_e32 v29, 31, v28
	v_ashrrev_i32_e32 v31, 31, v30
	v_ashrrev_i32_e32 v33, 31, v32
	v_ashrrev_i32_e32 v35, 31, v34
	v_ashrrev_i32_e32 v37, 31, v36
	v_lshlrev_b64 v[38:39], 12, v[38:39]
	v_lshl_add_u64 v[6:7], v[4:5], 0, v[6:7]
	v_lshlrev_b64 v[18:19], 12, v[18:19]
	v_lshlrev_b64 v[28:29], 12, v[28:29]
	v_lshlrev_b64 v[30:31], 12, v[30:31]
	v_lshlrev_b64 v[32:33], 12, v[32:33]
	v_lshlrev_b64 v[34:35], 12, v[34:35]
	v_lshlrev_b64 v[36:37], 12, v[36:37]
	v_lshl_add_u64 v[38:39], v[4:5], 0, v[38:39]
	v_lshl_add_u64 v[18:19], v[4:5], 0, v[18:19]
	v_lshl_add_u64 v[28:29], v[4:5], 0, v[28:29]
	v_lshl_add_u64 v[30:31], v[4:5], 0, v[30:31]
	v_lshl_add_u64 v[32:33], v[4:5], 0, v[32:33]
	v_lshl_add_u64 v[34:35], v[4:5], 0, v[34:35]
	v_lshl_add_u64 v[36:37], v[4:5], 0, v[36:37]
	global_load_dword v64, v[6:7], off
	global_load_dword v65, v[18:19], off
	global_load_dword v66, v[28:29], off
	global_load_dword v67, v[30:31], off
	global_load_dword v68, v[32:33], off
	global_load_dword v69, v[34:35], off
	global_load_dword v70, v[36:37], off
	global_load_dword v71, v[38:39], off
	v_or_b32_e32 v6, 8, v2
	v_ashrrev_i32_e32 v7, 31, v6
	v_or_b32_e32 v18, 9, v2
	v_or_b32_e32 v28, 10, v2
	v_or_b32_e32 v30, 11, v2
	v_or_b32_e32 v32, 12, v2
	v_or_b32_e32 v34, 13, v2
	v_or_b32_e32 v36, 14, v2
	v_or_b32_e32 v2, 15, v2
	v_lshlrev_b64 v[6:7], 12, v[6:7]
	v_ashrrev_i32_e32 v19, 31, v18
	v_ashrrev_i32_e32 v29, 31, v28
	v_ashrrev_i32_e32 v31, 31, v30
	v_ashrrev_i32_e32 v33, 31, v32
	v_ashrrev_i32_e32 v35, 31, v34
	v_ashrrev_i32_e32 v37, 31, v36
	v_ashrrev_i32_e32 v3, 31, v2
	v_lshl_add_u64 v[6:7], v[4:5], 0, v[6:7]
	v_lshlrev_b64 v[18:19], 12, v[18:19]
	v_lshlrev_b64 v[28:29], 12, v[28:29]
	v_lshlrev_b64 v[30:31], 12, v[30:31]
	v_lshlrev_b64 v[32:33], 12, v[32:33]
	v_lshlrev_b64 v[34:35], 12, v[34:35]
	v_lshlrev_b64 v[36:37], 12, v[36:37]
	v_lshlrev_b64 v[2:3], 12, v[2:3]
	v_lshl_add_u64 v[18:19], v[4:5], 0, v[18:19]
	v_lshl_add_u64 v[28:29], v[4:5], 0, v[28:29]
	v_lshl_add_u64 v[30:31], v[4:5], 0, v[30:31]
	v_lshl_add_u64 v[32:33], v[4:5], 0, v[32:33]
	v_lshl_add_u64 v[34:35], v[4:5], 0, v[34:35]
	v_lshl_add_u64 v[36:37], v[4:5], 0, v[36:37]
	v_lshl_add_u64 v[2:3], v[4:5], 0, v[2:3]
	global_load_dword v72, v[6:7], off
	global_load_dword v73, v[18:19], off
	global_load_dword v74, v[28:29], off
	global_load_dword v75, v[30:31], off
	global_load_dword v76, v[32:33], off
	global_load_dword v77, v[34:35], off
	global_load_dword v78, v[36:37], off
	global_load_dword v79, v[2:3], off
	v_add_u32_e32 v2, s21, v13
	v_ashrrev_i32_e32 v3, 31, v2
	v_lshlrev_b64 v[2:3], 11, v[2:3]
	v_lshl_add_u64 v[0:1], v[0:1], 0, v[2:3]
	v_add_co_u32_e32 v2, vcc, s34, v0
	s_nop 1
	v_addc_co_u32_e32 v3, vcc, 0, v1, vcc
	global_load_dwordx4 v[80:83], v[0:1], off
	global_load_dwordx4 v[84:87], v[2:3], off
	s_waitcnt vmcnt(0)
	s_branch .LBB0_865
.LBB0_864:
	s_or_b64 exec, exec, s[22:23]
	ds_write_b16 v98, v88 offset:34816
	ds_write_b16_d16_hi v98, v88 offset:34960
	ds_write_b16 v98, v89 offset:35104
	ds_write_b16_d16_hi v98, v89 offset:35248
	ds_write_b16 v98, v90 offset:35392
	ds_write_b16_d16_hi v98, v90 offset:35536
	ds_write_b16 v98, v91 offset:35680
	ds_write_b16_d16_hi v98, v91 offset:35824
	ds_write_b16 v97, v92 offset:34880
	ds_write_b16_d16_hi v97, v92 offset:35024
	ds_write_b16 v97, v93 offset:35168
	ds_write_b16_d16_hi v97, v93 offset:35312
	ds_write_b16 v97, v94 offset:35456
	ds_write_b16_d16_hi v97, v94 offset:35600
	ds_write_b16 v97, v95 offset:35744
	ds_write_b16_d16_hi v97, v95 offset:35888
	s_waitcnt lgkmcnt(0)
	s_barrier
	ds_read_b128 v[0:3], v25
	ds_read_b128 v[4:7], v25 offset:64
	ds_read_b128 v[28:31], v26 offset:34816
	ds_read_b128 v[32:35], v26 offset:34880
	s_waitcnt lgkmcnt(1)
	v_mfma_f32_16x16x32_bf16 v[28:31], v[0:3], v[28:31], 0
	ds_read_b128 v[36:39], v103 offset:37120
	s_ashr_i32 s21, s20, 31
	s_lshl_b64 s[22:23], s[20:21], 15
	s_waitcnt lgkmcnt(1)
	v_mfma_f32_16x16x32_bf16 v[28:31], v[4:7], v[32:35], v[28:31]
	ds_read_b128 v[32:35], v103 offset:37184
	v_lshl_or_b32 v40, v12, 8, s22
	v_mov_b32_e32 v41, s23
	s_waitcnt lgkmcnt(1)
	v_mfma_f32_16x16x32_bf16 v[36:39], v[0:3], v[36:39], 0
	v_lshl_add_u64 v[44:45], v[14:15], 0, v[40:41]
	s_nop 1
	v_cvt_pk_bf16_f32 v18, v28, v29
	v_cvt_pk_bf16_f32 v19, v30, v31
	ds_read_b128 v[28:31], v104 offset:39424
	s_waitcnt lgkmcnt(1)
	v_mfma_f32_16x16x32_bf16 v[32:35], v[4:7], v[32:35], v[36:39]
	ds_read_b128 v[40:43], v105 offset:41728
	global_store_dwordx2 v[44:45], v[18:19], off
	v_add_co_u32_e32 v46, vcc, s35, v44
	ds_read_b128 v[36:39], v104 offset:39488
	s_waitcnt lgkmcnt(2)
	v_mfma_f32_16x16x32_bf16 v[28:31], v[0:3], v[28:31], 0
	s_nop 1
	v_cvt_pk_bf16_f32 v18, v32, v33
	v_cvt_pk_bf16_f32 v19, v34, v35
	ds_read_b128 v[32:35], v105 offset:41792
	s_waitcnt lgkmcnt(1)
	v_mfma_f32_16x16x32_bf16 v[28:31], v[4:7], v[36:39], v[28:31]
	v_addc_co_u32_e32 v47, vcc, 0, v45, vcc
	global_store_dwordx2 v[46:47], v[18:19], off offset:-4096
	v_mfma_f32_16x16x32_bf16 v[36:39], v[0:3], v[40:43], 0
	ds_read_b128 v[40:43], v26 offset:44096
	s_nop 3
	v_cvt_pk_bf16_f32 v18, v28, v29
	v_cvt_pk_bf16_f32 v19, v30, v31
	s_waitcnt lgkmcnt(1)
	v_mfma_f32_16x16x32_bf16 v[32:35], v[4:7], v[32:35], v[36:39]
	ds_read_b128 v[28:31], v103 offset:46400
	global_store_dwordx2 v[46:47], v[18:19], off
	v_add_co_u32_e32 v46, vcc, s36, v44
	ds_read_b128 v[36:39], v26 offset:44032
	s_waitcnt lgkmcnt(2)
	v_mfma_f32_16x16x32_bf16 v[40:43], v[0:3], v[40:43], 0
	s_nop 1
	v_cvt_pk_bf16_f32 v18, v32, v33
	v_cvt_pk_bf16_f32 v19, v34, v35
	ds_read_b128 v[32:35], v103 offset:46336
	s_waitcnt lgkmcnt(1)
	v_mfma_f32_16x16x32_bf16 v[36:39], v[4:7], v[36:39], v[40:43]
	v_addc_co_u32_e32 v47, vcc, 0, v45, vcc
	global_store_dwordx2 v[46:47], v[18:19], off offset:-4096
	v_mfma_f32_16x16x32_bf16 v[28:31], v[0:3], v[28:31], 0
	ds_read_b128 v[40:43], v104 offset:48704
	s_nop 3
	v_cvt_pk_bf16_f32 v18, v36, v37
	v_cvt_pk_bf16_f32 v19, v38, v39
	s_waitcnt lgkmcnt(1)
	v_mfma_f32_16x16x32_bf16 v[28:31], v[4:7], v[32:35], v[28:31]
	ds_read_b128 v[32:35], v104 offset:48640
	global_store_dwordx2 v[46:47], v[18:19], off
	s_add_i32 s20, s20, s86
	s_waitcnt lgkmcnt(1)
	v_mfma_f32_16x16x32_bf16 v[36:39], v[0:3], v[40:43], 0
	v_add_co_u32_e32 v40, vcc, s37, v44
	s_nop 1
	v_cvt_pk_bf16_f32 v18, v28, v29
	v_cvt_pk_bf16_f32 v19, v30, v31
	s_waitcnt lgkmcnt(0)
	v_mfma_f32_16x16x32_bf16 v[28:31], v[4:7], v[32:35], v[36:39]
	ds_read_b128 v[32:35], v105 offset:51008
	v_addc_co_u32_e32 v41, vcc, 0, v45, vcc
	s_nop 0
	ds_read_b128 v[36:39], v105 offset:50944
	s_waitcnt lgkmcnt(1)
	v_mfma_f32_16x16x32_bf16 v[0:3], v[0:3], v[32:35], 0
	s_add_i32 s38, s38, s54
	s_add_i32 s24, s24, s25
	global_store_dwordx2 v[40:41], v[18:19], off offset:-4096
	s_waitcnt lgkmcnt(0)
	v_mfma_f32_16x16x32_bf16 v[0:3], v[4:7], v[36:39], v[0:3]
	v_cvt_pk_bf16_f32 v18, v28, v29
	v_cvt_pk_bf16_f32 v19, v30, v31
	s_cmpk_gt_i32 s20, 0xfff
	v_add_u32_e32 v16, s27, v16
	global_store_dwordx2 v[40:41], v[18:19], off
	s_nop 2
	v_cvt_pk_bf16_f32 v0, v0, v1
	v_cvt_pk_bf16_f32 v1, v2, v3
	v_add_co_u32_e32 v2, vcc, 0x7000, v44
	s_nop 1
	v_addc_co_u32_e32 v3, vcc, 0, v45, vcc
	global_store_dwordx2 v[2:3], v[0:1], off
	s_barrier
	s_cbranch_scc1 .LBB0_867
